# attention softmax segment: removed zero-init adds, no-op kaug selects, empty-asm pad nops; dq on diagonal path only; scalar side-change shortcut
# speedup vs baseline: 1.0166x; 1.0163x over previous
; #define ATT_SB() __builtin_amdgcn_sched_barrier(0)
;     ...
;     for (int i = 1; i < NTe; ++i) {
;         const int tau = ATT_TAU(i), slot = i & 3;
;         { const int id_ = i + 2 < NTe ? i + 2 : NTe - 1; ATT_DMA(id_, (i + 2) & 3); }
;         { const lds_cptr vp = vp0 + ((i - 1) & 3) * SLOTB, kp = kp0 + slot * SLOTB;
;           ATT_VFR(a, 0); ATT_VFR(b, 1);
;           const bf16x8 ka0 = ATT_KA(0), ka1 = ATT_KA(2048), ka2 = ATT_KB(0), ka3 = ATT_KB(2048);
;           ATT_SB();
;           ATT_PVK(a, pa0, pb0); ATT_SB();
;           ATT_VFR(c, 2); ATT_SB();
;           ATT_PVK(b, pa1, pb1); ATT_SB();
;           ATT_VFR(d, 3);
;           const bf16x8 kb0 = ATT_KA(4096), kb1 = ATT_KA(6144), kb2 = ATT_KB(4096), kb3 = ATT_KB(6144);
;           ATT_LDQ();
;           ATT_SB();
;           ATT_PVK(c, pa2, pb2); ATT_SB();
;           ATT_PVK(d, pa3, pb3); ATT_SB();
;           ATT_QKA(); ATT_QKB(); }
;         ATT_SB();
;         ATT_BARV(2);
;         __builtin_amdgcn_s_setprio(1);
;         ATT_SB();
;         { const bool diag = tau == td; const float dq = (float)(tq - tau * KVBLK);
;           if (ABL & 2) { asm volatile("" : "=v"(pa0), "=v"(pa1), "=v"(pa2), "=v"(pa3), "=v"(pb0), "=v"(pb1), "=v"(pb2), "=v"(pb3) : "v"(sa0), "v"(sa1), "v"(sb0), "v"(sb1)); } else {
;           if (diag) { ATT_DIAG_BIAS(sa0, sa1); ATT_DIAG_BIAS(sb0, sb1); }
;           const float big = (float)(1u << THRL);
;           bool redo = false;
;           { float accA; ATT_EXPSUM(sa0, sa1, accA);
;             if (__builtin_expect(__any(!(accA < big)), 0)) { const lds_cptr kp = kp0 + slot * SLOTB;
;                 const bf16x8 ka0 = ATT_KA(0), ka1 = ATT_KA(2048), ka2 = ATT_KB(0), ka3 = ATT_KB(2048);
;                 ATT_LDQ();
;                 ATT_QKA(); asm volatile("s_nop 15\n\ts_nop 7" : "+v"(sa0), "+v"(sa1)); if (diag) ATT_DIAG_BIAS(sa0, sa1);
;                 accA = softmax_exact<false>(sa0, sa1, mhatA, lA, oa0, oa1, wsf, r32, hi); redo = true; }
;             lA += accA; ATT_PACK(sa0, sa1, pa0, pa1, pa2, pa3); }
;           ATT_SB();
;           { float accB; ATT_EXPSUM(sb0, sb1, accB);
;             if (__builtin_expect(__any(!(accB < big)), 0)) { const lds_cptr kp = kp0 + slot * SLOTB;
;                 const bf16x8 kb0 = ATT_KA(4096), kb1 = ATT_KA(6144), kb2 = ATT_KB(4096), kb3 = ATT_KB(6144);
;                 ATT_LDQ();
.LBB0_338:
	s_lshl_b32 s30, s31, 6
	v_cvt_pk_bf16_f32 v103, v86, v87
	v_cvt_pk_bf16_f32 v86, v92, v93
	v_cvt_f32_i32_e32 v92, s30
	v_add_f32_e32 v153, v153, v79
	v_cvt_pk_bf16_f32 v100, v80, v81
	v_cvt_pk_bf16_f32 v101, v82, v83
	v_lshrrev_b32_e32 v93, 16, v92
	v_and_b32_e32 v92, 0xffff0000, v92
	v_or_b32_e32 v92, v93, v92
	v_cvt_pk_bf16_f32 v102, v84, v85
	v_cvt_pk_bf16_f32 v84, v88, v97
	v_cvt_pk_bf16_f32 v85, v90, v99
	v_cvt_pk_bf16_f32 v87, v94, v73
	v_cvt_pk_bf16_f32 v80, v64, v65
	v_cvt_pk_bf16_f32 v81, v66, v67
	v_cvt_pk_bf16_f32 v82, v68, v69
	v_cvt_pk_bf16_f32 v83, v70, v71
	v_cvt_pk_bf16_f32 v64, v72, v89
	v_cvt_pk_bf16_f32 v65, v74, v91
	v_cvt_pk_bf16_f32 v66, v76, v77
	v_cvt_pk_bf16_f32 v67, v78, v75
	v_cvt_pk_bf16_f32 v88, v193, v158
	v_cvt_pk_bf16_f32 v89, v194, v112
	v_cvt_pk_bf16_f32 v90, v195, v114
	v_cvt_pk_bf16_f32 v91, v198, v160
	v_cvt_pk_bf16_f32 v76, v161, v162
	v_cvt_pk_bf16_f32 v77, v163, v120
	v_cvt_pk_bf16_f32 v78, v121, v122
	v_cvt_pk_bf16_f32 v79, v123, v124
	v_cvt_pk_bf16_f32 v72, v192, v128
	v_cvt_pk_bf16_f32 v73, v159, v96
	v_cvt_pk_bf16_f32 v74, v113, v98
	v_cvt_pk_bf16_f32 v75, v115, v116
	v_cvt_pk_bf16_f32 v68, v117, v118
	v_cvt_pk_bf16_f32 v69, v119, v104
	v_cvt_pk_bf16_f32 v70, v105, v106
	v_cvt_pk_bf16_f32 v71, v107, v108
	v_add_f32_e32 v152, v152, v109
	v_cndmask_b32_e64 v130, v92, v130, s[38:39]
	v_cndmask_b32_e64 v131, v93, v131, s[38:39]
	v_cndmask_b32_e64 v134, v92, v134, s[38:39]
	v_cndmask_b32_e64 v135, v93, v135, s[38:39]
	s_setprio 0
	s_waitcnt lgkmcnt(0)
	s_barrier
	s_addk_i32 s29, 0x2000
	s_add_i32 s27, s27, -1
	s_add_i32 s28, s28, 1
	s_cmp_eq_u32 s28, s26
	s_cbranch_scc1 .LBB0_367
.LBB0_339:
	s_add_i32 s30, s15, s28
	s_cmp_lt_i32 s28, s19
	s_cselect_b32 s30, s30, s27
	s_add_i32 s31, s28, 2
	s_cmp_lt_i32 s31, s20
	s_cselect_b32 s34, s31, s23
	s_add_i32 s35, s34, s15
	s_sub_i32 s36, s22, s34
	s_cmp_lt_i32 s34, s19
	s_cselect_b32 s36, s35, s36
	s_add_i32 s34, s29, 0xffffa000
	s_and_b32 s35, s29, 0x6000
	v_add_u32_e32 v112, s35, v191
	s_and_b32 s34, s34, 0x6000
	v_add_u32_e32 v197, s34, v181
	ds_read_b64_tr_b16 v[92:93], v112 offset:32768
	ds_read_b64_tr_b16 v[94:95], v112 offset:33280
	ds_read_b64_tr_b16 v[96:97], v112 offset:33792
	ds_read_b64_tr_b16 v[98:99], v112 offset:34304
	ds_read_b64_tr_b16 v[104:105], v112 offset:36864
	ds_read_b64_tr_b16 v[106:107], v112 offset:37376
	ds_read_b64_tr_b16 v[108:109], v112 offset:37888
	ds_read_b64_tr_b16 v[110:111], v112 offset:38400
	ds_read_b128 v[158:161], v197
	ds_read_b128 v[192:195], v197 offset:2048
	v_add_u32_e32 v196, v197, v183
	ds_read_b128 v[198:201], v196
	ds_read_b128 v[202:205], v196 offset:2048
	s_waitcnt lgkmcnt(10)
	v_mfma_f32_32x32x16_bf16 v[48:63], v[88:91], v[92:95], v[48:63]
	s_waitcnt lgkmcnt(6)
	v_mfma_f32_32x32x16_bf16 v[32:47], v[88:91], v[104:107], v[32:47]
	v_mfma_f32_32x32x16_bf16 v[16:31], v[100:103], v[92:95], v[16:31]
	v_mfma_f32_32x32x16_bf16 v[0:15], v[100:103], v[104:107], v[0:15]
	v_mad_i64_i32 v[92:93], s[34:35], s36, v224, v[148:149]
	s_add_i32 s34, s29, 0xffffe000
	s_and_b32 s37, s34, 0x6000
	s_add_i32 s34, s37, s45
	s_mov_b32 s35, m0
	s_mov_b32 m0, s34
	s_nop 0
	global_load_lds_dwordx4 v[92:93], off
	s_mov_b32 m0, s35
	s_nop 0
	v_mad_i64_i32 v[92:93], s[34:35], s36, v224, v[146:147]
	s_add_i32 s34, s37, s18
	s_mov_b32 s35, m0
	s_mov_b32 m0, s34
	s_nop 0
	global_load_lds_dwordx4 v[92:93], off
	s_mov_b32 m0, s35
	ds_read_b64_tr_b16 v[88:89], v112 offset:34816
	ds_read_b64_tr_b16 v[90:91], v112 offset:35328
	ds_read_b64_tr_b16 v[92:93], v112 offset:38912
	ds_read_b64_tr_b16 v[94:95], v112 offset:39424
	v_mfma_f32_32x32x16_bf16 v[48:63], v[76:79], v[96:99], v[48:63]
	s_waitcnt lgkmcnt(8)
	v_mfma_f32_32x32x16_bf16 v[32:47], v[76:79], v[108:111], v[32:47]
	v_mfma_f32_32x32x16_bf16 v[16:31], v[84:87], v[96:99], v[16:31]
	v_mfma_f32_32x32x16_bf16 v[0:15], v[84:87], v[108:111], v[0:15]
	ds_read_b64_tr_b16 v[76:77], v112 offset:35840
	ds_read_b64_tr_b16 v[78:79], v112 offset:36352
	ds_read_b64_tr_b16 v[84:85], v112 offset:39936
	ds_read_b64_tr_b16 v[86:87], v112 offset:40448
	ds_read_b128 v[206:209], v197 offset:4096
	ds_read_b128 v[228:231], v197 offset:6144
	ds_read_b128 v[232:235], v196 offset:4096
	ds_read_b128 v[236:239], v196 offset:6144
	ds_read_b128 v[240:243], v174
	ds_read_b128 v[244:247], v174 offset:1024
	ds_read_b128 v[248:251], v174 offset:2048
	ds_read_b128 v[186:189], v174 offset:3072
	s_waitcnt lgkmcnt(14)
	v_mfma_f32_32x32x16_bf16 v[48:63], v[72:75], v[88:91], v[48:63]
	s_waitcnt lgkmcnt(12)
	v_mfma_f32_32x32x16_bf16 v[32:47], v[72:75], v[92:95], v[32:47]
	v_mfma_f32_32x32x16_bf16 v[16:31], v[80:83], v[88:91], v[16:31]
	v_mfma_f32_32x32x16_bf16 v[0:15], v[80:83], v[92:95], v[0:15]
	s_waitcnt lgkmcnt(10)
	v_mfma_f32_32x32x16_bf16 v[48:63], v[68:71], v[76:79], v[48:63]
	s_waitcnt lgkmcnt(8)
	v_mfma_f32_32x32x16_bf16 v[32:47], v[68:71], v[84:87], v[32:47]
	v_mfma_f32_32x32x16_bf16 v[16:31], v[64:67], v[76:79], v[16:31]
	v_mfma_f32_32x32x16_bf16 v[0:15], v[64:67], v[84:87], v[0:15]
	v_mfma_f32_32x32x16_bf16 v[112:127], v[134:137], v[142:145], 0
	v_mfma_f32_32x32x16_bf16 v[96:111], v[130:133], v[142:145], 0
	v_mfma_f32_32x32x16_bf16 v[80:95], v[134:137], v[138:141], 0
	v_mfma_f32_32x32x16_bf16 v[64:79], v[130:133], v[138:141], 0
	s_waitcnt lgkmcnt(3)
	v_mfma_f32_32x32x16_bf16 v[112:127], v[158:161], v[240:243], v[112:127]
	v_mfma_f32_32x32x16_bf16 v[96:111], v[192:195], v[240:243], v[96:111]
	s_waitcnt lgkmcnt(1)
	v_mfma_f32_32x32x16_bf16 v[80:95], v[206:209], v[248:251], v[80:95]
	v_mfma_f32_32x32x16_bf16 v[64:79], v[228:231], v[248:251], v[64:79]
	v_mfma_f32_32x32x16_bf16 v[112:127], v[198:201], v[244:247], v[112:127]
	v_mfma_f32_32x32x16_bf16 v[96:111], v[202:205], v[244:247], v[96:111]
	s_waitcnt lgkmcnt(0)
	v_mfma_f32_32x32x16_bf16 v[80:95], v[232:235], v[186:189], v[80:95]
	v_mfma_f32_32x32x16_bf16 v[64:79], v[236:239], v[186:189], v[64:79]
	s_cmp_eq_u32 s30, s21
	s_cselect_b64 s[42:43], -1, 0
	s_cmp_lg_u32 s30, s21
	s_waitcnt vmcnt(2) lgkmcnt(0)
	s_barrier
; #define ATT_DIAG_BIAS(s0, s1) do { const float dqh_ = dq - (float)(4 * hi); _Pragma("unroll") for (int r = 0; r < 16; ++r) { const float c_ = (float)((r & 3) + 8 * (r >> 2)); \
;         s0[r] = __builtin_fmaf(-sl, __builtin_fabsf(dqh_ - c_), s0[r]); s1[r] = __builtin_fmaf(-sl, __builtin_fabsf(dqh_ - (c_ + 32.f)), s1[r]); } } while (0)
;     ...
;         { const bool diag = tau == td; const float dq = (float)(tq - tau * KVBLK);
;           if (ABL & 2) { asm volatile("" : "=v"(pa0), "=v"(pa1), "=v"(pa2), "=v"(pa3), "=v"(pb0), "=v"(pb1), "=v"(pb2), "=v"(pb3) : "v"(sa0), "v"(sa1), "v"(sb0), "v"(sb1)); } else {
;           if (diag) { ATT_DIAG_BIAS(sa0, sa1); ATT_DIAG_BIAS(sb0, sb1); }
	s_setprio 1
	s_nop 1
	s_cbranch_scc1 .LBB0_341
	s_lshl_b32 s34, s30, 6
	v_subrev_u32_e32 v128, s34, v171
	v_cvt_f32_i32_e32 v199, v128
	s_mov_b32 s34, 0xc2000000
	v_sub_f32_e32 v128, v199, v184
	s_mov_b32 s35, 0xc2040000
	v_pk_add_f32 v[158:159], v[128:129], s[34:35] op_sel_hi:[0,1]
	s_mov_b32 s34, -2.0
	s_mov_b32 s35, 0xc0400000
	v_pk_add_f32 v[160:161], v[128:129], s[34:35] op_sel_hi:[0,1]
	s_mov_b32 s34, 0xc2080000
	s_mov_b32 s35, 0xc20c0000
	v_pk_add_f32 v[162:163], v[128:129], s[34:35] op_sel_hi:[0,1]
	s_mov_b32 s34, 0xc1000000
	s_mov_b32 s35, 0xc1100000
	v_pk_add_f32 v[186:187], v[128:129], s[34:35] op_sel_hi:[0,1]
	s_mov_b32 s34, 0xc2200000
	s_mov_b32 s35, 0xc2240000
	v_pk_add_f32 v[188:189], v[128:129], s[34:35] op_sel_hi:[0,1]
	s_mov_b32 s34, 0xc1200000
	s_mov_b32 s35, 0xc1300000
	v_pk_add_f32 v[192:193], v[128:129], s[34:35] op_sel_hi:[0,1]
	s_mov_b32 s34, 0xc2280000
	s_mov_b32 s35, 0xc22c0000
	v_pk_add_f32 v[194:195], v[128:129], s[34:35] op_sel_hi:[0,1]
	s_mov_b32 s34, 0xc1800000
	s_mov_b32 s35, 0xc1880000
	v_pk_add_f32 v[200:201], v[128:129], s[34:35] op_sel_hi:[0,1]
	s_mov_b32 s34, 0xc2400000
	s_mov_b32 s35, 0xc2440000
	v_pk_add_f32 v[202:203], v[128:129], s[34:35] op_sel_hi:[0,1]
	s_mov_b32 s34, 0xc1900000
	s_mov_b32 s35, 0xc1980000
	v_pk_add_f32 v[204:205], v[128:129], s[34:35] op_sel_hi:[0,1]
	s_mov_b32 s34, 0xc2480000
	s_mov_b32 s35, 0xc24c0000
	v_pk_add_f32 v[206:207], v[128:129], s[34:35] op_sel_hi:[0,1]
	s_mov_b32 s34, 0xc1c00000
	s_mov_b32 s35, 0xc1c80000
	v_pk_add_f32 v[208:209], v[128:129], s[34:35] op_sel_hi:[0,1]
	s_mov_b32 s34, 0xc2600000
	s_mov_b32 s35, 0xc2640000
	v_pk_add_f32 v[210:211], v[128:129], s[34:35] op_sel_hi:[0,1]
	s_mov_b32 s34, 0xc1d00000
	s_mov_b32 s35, 0xc1d80000
	v_pk_add_f32 v[214:215], v[128:129], s[34:35] op_sel_hi:[0,1]
	s_mov_b32 s34, 0xc2680000
	s_mov_b32 s35, 0xc26c0000
	v_add_f32_e32 v155, -1.0, v128
	v_pk_add_f32 v[222:223], v[128:129], s[34:35] op_sel_hi:[0,1]
	v_and_b32_e32 v159, 0x7fffffff, v159
	v_and_b32_e32 v158, 0x7fffffff, v158
	v_and_b32_e32 v163, 0x7fffffff, v163
	v_and_b32_e32 v162, 0x7fffffff, v162
	v_and_b32_e32 v187, 0x7fffffff, v187
	v_and_b32_e32 v186, 0x7fffffff, v186
	v_and_b32_e32 v189, 0x7fffffff, v189
	v_and_b32_e32 v188, 0x7fffffff, v188
	v_and_b32_e32 v193, 0x7fffffff, v193
	v_and_b32_e32 v192, 0x7fffffff, v192
	v_and_b32_e32 v195, 0x7fffffff, v195
	v_and_b32_e32 v194, 0x7fffffff, v194
	v_and_b32_e32 v201, 0x7fffffff, v201
	v_and_b32_e32 v200, 0x7fffffff, v200
	v_and_b32_e32 v203, 0x7fffffff, v203
	v_and_b32_e32 v202, 0x7fffffff, v202
	v_and_b32_e32 v205, 0x7fffffff, v205
	v_and_b32_e32 v204, 0x7fffffff, v204
	v_and_b32_e32 v207, 0x7fffffff, v207
	v_and_b32_e32 v206, 0x7fffffff, v206
	v_and_b32_e32 v209, 0x7fffffff, v209
	v_and_b32_e32 v208, 0x7fffffff, v208
	v_and_b32_e32 v211, 0x7fffffff, v211
	v_and_b32_e32 v210, 0x7fffffff, v210
	v_and_b32_e32 v215, 0x7fffffff, v215
	v_and_b32_e32 v214, 0x7fffffff, v214
	v_and_b32_e32 v223, 0x7fffffff, v223
	v_and_b32_e32 v222, 0x7fffffff, v222
	v_and_b32_e32 v161, 0x7fffffff, v161
	v_and_b32_e32 v160, 0x7fffffff, v160
	v_and_b32_e32 v228, 0x7fffffff, v128
	v_and_b32_e32 v229, 0x7fffffff, v155
	v_mov_b32_e32 v155, v154
	v_pk_fma_f32 v[94:95], v[154:155], v[214:215], v[94:95]
	v_pk_fma_f32 v[92:93], v[154:155], v[208:209], v[92:93]
	v_pk_fma_f32 v[90:91], v[154:155], v[204:205], v[90:91]
	v_pk_fma_f32 v[88:89], v[154:155], v[200:201], v[88:89]
	v_pk_fma_f32 v[86:87], v[154:155], v[192:193], v[86:87]
	v_pk_fma_f32 v[84:85], v[154:155], v[186:187], v[84:85]
	v_pk_fma_f32 v[82:83], v[154:155], v[160:161], v[82:83]
	v_pk_fma_f32 v[80:81], v[156:157], v[228:229], v[80:81]
	v_pk_fma_f32 v[78:79], v[154:155], v[222:223], v[78:79]
	v_pk_fma_f32 v[76:77], v[154:155], v[210:211], v[76:77]
	v_pk_fma_f32 v[74:75], v[154:155], v[206:207], v[74:75]
	v_pk_fma_f32 v[72:73], v[154:155], v[202:203], v[72:73]
	v_pk_fma_f32 v[70:71], v[154:155], v[194:195], v[70:71]
	v_pk_fma_f32 v[68:69], v[154:155], v[188:189], v[68:69]
	v_pk_fma_f32 v[66:67], v[154:155], v[162:163], v[66:67]
	v_pk_fma_f32 v[64:65], v[156:157], v[158:159], v[64:65]
	v_pk_fma_f32 v[126:127], v[154:155], v[214:215], v[126:127]
	v_pk_fma_f32 v[124:125], v[154:155], v[208:209], v[124:125]
	v_pk_fma_f32 v[122:123], v[154:155], v[204:205], v[122:123]
	v_pk_fma_f32 v[120:121], v[154:155], v[200:201], v[120:121]
	v_pk_fma_f32 v[118:119], v[154:155], v[192:193], v[118:119]
	v_pk_fma_f32 v[116:117], v[154:155], v[186:187], v[116:117]
	v_pk_fma_f32 v[114:115], v[154:155], v[160:161], v[114:115]
	v_pk_fma_f32 v[112:113], v[156:157], v[228:229], v[112:113]
	v_pk_fma_f32 v[110:111], v[154:155], v[222:223], v[110:111]
	v_pk_fma_f32 v[108:109], v[154:155], v[210:211], v[108:109]
	v_pk_fma_f32 v[106:107], v[154:155], v[206:207], v[106:107]
	v_pk_fma_f32 v[104:105], v[154:155], v[202:203], v[104:105]
	v_pk_fma_f32 v[102:103], v[154:155], v[194:195], v[102:103]
	v_pk_fma_f32 v[100:101], v[154:155], v[188:189], v[100:101]
	v_pk_fma_f32 v[98:99], v[154:155], v[162:163], v[98:99]
	v_pk_fma_f32 v[96:97], v[156:157], v[158:159], v[96:97]
; #define ATT_DIAG_BIAS(s0, s1) do { const float dqh_ = dq - (float)(4 * hi); _Pragma("unroll") for (int r = 0; r < 16; ++r) { const float c_ = (float)((r & 3) + 8 * (r >> 2)); \
;         s0[r] = __builtin_fmaf(-sl, __builtin_fabsf(dqh_ - c_), s0[r]); s1[r] = __builtin_fmaf(-sl, __builtin_fabsf(dqh_ - (c_ + 32.f)), s1[r]); } } while (0)
; #define ATT_SB() __builtin_amdgcn_sched_barrier(0)
; #define ATT_LDQ() const bf16x8 qf0 = *(const __attribute__((address_space(3))) bf16x8*)(qp), qf1 = *(const __attribute__((address_space(3))) bf16x8*)(qp + 1024), qf2 = *(const __attribute__((address_space(3))) bf16x8*)(qp + 2048), qf3 = *(const __attribute__((address_space(3))) bf16x8*)(qp + 3072)
; #define ATT_KA(off) (*(const __attribute__((address_space(3))) bf16x8*)(kp + (off)))
; #define ATT_KB(off) (*(const __attribute__((address_space(3))) bf16x8*)(kp + koB + (off)))
;     ...
;           { float accA; ATT_EXPSUM(sa0, sa1, accA);
;             if (__builtin_expect(__any(!(accA < big)), 0)) { const lds_cptr kp = kp0 + slot * SLOTB;
;                 const bf16x8 ka0 = ATT_KA(0), ka1 = ATT_KA(2048), ka2 = ATT_KB(0), ka3 = ATT_KB(2048);
;                 ATT_LDQ();
;                 ATT_QKA(); asm volatile("s_nop 15\n\ts_nop 7" : "+v"(sa0), "+v"(sa1)); if (diag) ATT_DIAG_BIAS(sa0, sa1);
;                 accA = softmax_exact<false>(sa0, sa1, mhatA, lA, oa0, oa1, wsf, r32, hi); redo = true; }
;             lA += accA; ATT_PACK(sa0, sa1, pa0, pa1, pa2, pa3); }
;           ATT_SB();
;           { float accB; ATT_EXPSUM(sb0, sb1, accB);
;             if (__builtin_expect(__any(!(accB < big)), 0)) { const lds_cptr kp = kp0 + slot * SLOTB;
;                 const bf16x8 kb0 = ATT_KA(4096), kb1 = ATT_KA(6144), kb2 = ATT_KB(4096), kb3 = ATT_KB(6144);
;                 ATT_LDQ();
;                 ATT_QKB(); asm volatile("s_nop 15\n\ts_nop 7" : "+v"(sb0), "+v"(sb1)); if (diag) ATT_DIAG_BIAS(sb0, sb1);
;                 accB = softmax_exact<false>(sb0, sb1, mhatB, lB, ob0, ob1, wsf + 32, r32, hi); redo = true; }
;             lB += accB; ATT_PACK(sb0, sb1, pb0, pb1, pb2, pb3); }
;           { const int in_ = i + 1 < NTe ? i + 1 : i; const int tn_ = ATT_TAU(in_); const int sdn_ = ATT_SIDE(tn_);
;             if (redo || sdn_ != ATT_SIDE(tau)) { ATT_QAUG(sdn_); }
;             ATT_KAUG(tn_); } } }
.LBB0_341:
	v_exp_f32_e32 v193, v112
	v_exp_f32_e32 v192, v96
	v_exp_f32_e32 v158, v113
	v_exp_f32_e32 v128, v97
	v_exp_f32_e32 v194, v114
	v_exp_f32_e32 v159, v98
	v_exp_f32_e32 v112, v115
	v_exp_f32_e32 v114, v117
	v_exp_f32_e32 v96, v99
	v_add_f32_e32 v97, v194, v193
	v_add_f32_e32 v99, v192, v159
	v_add_f32_e32 v115, v112, v158
	v_exp_f32_e32 v195, v116
	v_exp_f32_e32 v113, v100
	v_exp_f32_e32 v98, v101
	v_add_f32_e32 v100, v114, v115
	v_exp_f32_e32 v198, v118
	v_exp_f32_e32 v115, v102
	v_add_f32_e32 v155, v96, v128
	v_exp_f32_e32 v160, v119
	v_exp_f32_e32 v116, v103
	v_add_f32_e32 v97, v195, v97
	v_add_f32_e32 v99, v113, v99
	v_exp_f32_e32 v161, v120
	v_exp_f32_e32 v117, v104
	v_exp_f32_e32 v162, v121
	v_add_f32_e32 v101, v98, v155
	v_exp_f32_e32 v118, v105
	v_add_f32_e32 v97, v198, v97
	v_add_f32_e32 v99, v115, v99
	v_exp_f32_e32 v163, v122
	v_exp_f32_e32 v119, v106
	v_add_f32_e32 v100, v160, v100
	v_add_f32_e32 v101, v116, v101
	v_exp_f32_e32 v120, v123
	v_exp_f32_e32 v104, v107
	v_add_f32_e32 v97, v161, v97
	v_add_f32_e32 v99, v117, v99
	v_exp_f32_e32 v121, v124
	v_exp_f32_e32 v105, v108
	v_add_f32_e32 v100, v162, v100
	v_add_f32_e32 v101, v118, v101
	v_exp_f32_e32 v122, v125
	v_exp_f32_e32 v106, v109
	v_add_f32_e32 v97, v163, v97
	v_add_f32_e32 v99, v119, v99
	v_exp_f32_e32 v123, v126
	v_exp_f32_e32 v107, v110
	v_add_f32_e32 v100, v120, v100
	v_add_f32_e32 v101, v104, v101
	v_exp_f32_e32 v124, v127
	v_exp_f32_e32 v108, v111
	v_add_f32_e32 v97, v121, v97
	v_add_f32_e32 v99, v105, v99
	v_add_f32_e32 v100, v122, v100
	v_add_f32_e32 v101, v106, v101
	v_add_f32_e32 v97, v123, v97
	v_add_f32_e32 v99, v107, v99
	v_add_f32_e32 v100, v124, v100
	v_add_f32_e32 v101, v108, v101
	v_add_f32_e32 v97, v97, v99
	v_add_f32_e32 v99, v100, v101
	v_add_f32_e32 v109, v97, v99
	v_cmp_ngt_f32_e32 vcc, s7, v109
	s_cmp_lg_u64 vcc, 0
	s_cselect_b64 s[62:63], -1, 0
	s_cbranch_vccnz .LBB0_357
.LBB0_342:
	v_exp_f32_e32 v80, v80
	v_exp_f32_e32 v64, v64
	v_exp_f32_e32 v81, v81
	v_exp_f32_e32 v65, v65
	v_exp_f32_e32 v82, v82
	v_exp_f32_e32 v66, v66
	v_exp_f32_e32 v83, v83
	v_exp_f32_e32 v67, v67
	v_exp_f32_e32 v84, v84
	v_add_f32_e32 v97, v82, v80
	v_exp_f32_e32 v68, v68
	v_exp_f32_e32 v85, v85
	v_exp_f32_e32 v69, v69
	v_exp_f32_e32 v86, v86
	v_exp_f32_e32 v70, v70
	v_add_f32_e32 v99, v66, v64
	v_add_f32_e32 v100, v83, v81
	v_add_f32_e32 v101, v67, v65
	v_add_f32_e32 v97, v84, v97
	v_exp_f32_e32 v88, v88
	v_exp_f32_e32 v87, v87
	v_add_f32_e32 v99, v68, v99
	v_add_f32_e32 v100, v85, v100
	v_add_f32_e32 v101, v69, v101
	v_add_f32_e32 v97, v86, v97
	v_exp_f32_e32 v71, v71
	v_exp_f32_e32 v72, v72
	v_exp_f32_e32 v90, v90
	v_add_f32_e32 v99, v70, v99
	v_add_f32_e32 v102, v88, v97
	v_exp_f32_e32 v97, v89
	v_exp_f32_e32 v89, v73
	v_exp_f32_e32 v74, v74
	v_add_f32_e32 v100, v87, v100
	v_add_f32_e32 v101, v71, v101
	v_add_f32_e32 v99, v72, v99
	v_exp_f32_e32 v92, v92
	v_add_f32_e32 v73, v89, v101
	v_add_f32_e32 v101, v90, v102
	v_add_f32_e32 v102, v74, v99
	v_exp_f32_e32 v99, v91
	v_exp_f32_e32 v91, v75
	v_add_f32_e32 v100, v97, v100
	v_exp_f32_e32 v76, v76
	v_exp_f32_e32 v93, v93
	v_exp_f32_e32 v77, v77
	v_exp_f32_e32 v94, v94
	v_exp_f32_e32 v78, v78
	v_add_f32_e32 v100, v99, v100
	v_add_f32_e32 v73, v91, v73
	v_add_f32_e32 v75, v92, v101
	v_add_f32_e32 v101, v76, v102
	v_add_f32_e32 v100, v93, v100
	v_add_f32_e32 v102, v77, v73
	v_add_f32_e32 v73, v94, v75
	v_add_f32_e32 v75, v78, v101
	v_add_f32_e32 v101, v73, v75
	v_exp_f32_e32 v73, v95
	v_exp_f32_e32 v75, v79
	v_add_f32_e32 v79, v73, v100
	v_add_f32_e32 v95, v75, v102
	v_add_f32_e32 v79, v79, v95
	v_add_f32_e32 v79, v101, v79
	v_cmp_ngt_f32_e32 vcc, s7, v79
	s_cbranch_vccnz .LBB0_362
.LBB0_343:
	s_add_i32 s31, s31, -1
	s_cmp_lt_i32 s31, s20
	s_cselect_b32 s31, s31, s28
	s_add_i32 s34, s31, s15
	s_sub_i32 s35, s22, s31
	s_cmp_lt_i32 s31, s19
	s_cselect_b32 s31, s34, s35
	s_sub_i32 s34, s30, s21
	s_sub_i32 s35, s31, s21
	s_mul_i32 s34, s34, s35
	s_cmp_lt_i32 s34, 1
	s_cbranch_scc1 .Latt_side_slow
	s_and_b64 vcc, exec, s[62:63]
	s_mov_b64 s[34:35], s[74:75]
	s_cbranch_vccz .LBB0_338
.Latt_side_slow:
	s_cmp_lt_i32 s31, s21
	s_cselect_b64 s[40:41], -1, 0
	s_cmp_ge_i32 s31, s21
	s_cselect_b64 s[64:65], -1, 0
	s_cmp_eq_u32 s31, s21
	s_cselect_b64 s[58:59], -1, 0
	s_cmp_lg_u32 s31, s21
	s_cselect_b64 s[36:37], -1, 0
	s_and_b64 vcc, exec, s[62:63]
	s_cbranch_vccnz .LBB0_345
	s_xor_b64 s[34:35], s[42:43], s[58:59]
	s_nor_b64 s[34:35], s[40:41], s[34:35]
	s_cmp_lt_i32 s30, s21
	v_cndmask_b32_e64 v95, 0, 1, s[34:35]
	v_cndmask_b32_e64 v100, 0, 1, s[40:41]
	s_cselect_b64 vcc, -1, 0
	v_cndmask_b32_e32 v95, v95, v100, vcc
	v_and_b32_e32 v95, 1, v95
	v_cmp_eq_u32_e32 vcc, 1, v95
	s_xor_b64 s[62:63], vcc, -1
